# attention tile: K-fragment LDS reads issued earlier in the tile, QK chain order changed so the last-loaded fragment is used last
# speedup vs baseline: 1.0132x; 1.0066x over previous
.LBB0_927:
	s_add_i32 s69, s68, -3
	s_add_i32 s10, s68, -4
	s_min_u32 s10, s10, s24
	s_lshl_b32 s10, s10, 15
	s_add_u32 s4, s20, s10
	s_addc_u32 s5, s21, 0
	ds_read_b64_tr_b16 v[224:225], v174
	ds_read_b64_tr_b16 v[226:227], v175 offset:2048
	ds_read_b64_tr_b16 v[228:229], v176
	ds_read_b64_tr_b16 v[230:231], v177 offset:2048
	ds_read_b64_tr_b16 v[232:233], v178
	ds_read_b64_tr_b16 v[234:235], v179 offset:2048
	ds_read_b64_tr_b16 v[236:237], v183
	ds_read_b64_tr_b16 v[238:239], v184 offset:2048
	s_mov_b32 m0, s53
	v_mfma_f32_32x32x16_bf16 v[96:111], v[132:135], v[116:119], v[64:79]
	global_load_lds_dwordx4 v163, s[4:5]
	s_mov_b32 m0, s58
	v_mfma_f32_32x32x16_bf16 v[96:111], v[140:143], v[120:123], v[96:111]
	global_load_lds_dwordx4 v254, s[4:5]
	s_mov_b32 m0, s59
	v_mfma_f32_32x32x16_bf16 v[96:111], v[148:151], v[124:127], v[96:111]
	global_load_lds_dwordx4 v255, s[22:23]
	ds_read_b64_tr_b16 v[132:133], v176 offset:4096
	ds_read_b64_tr_b16 v[134:135], v177 offset:6144
	s_mov_b32 m0, s61
	v_mfma_f32_32x32x16_bf16 v[96:111], v[80:83], v[112:115], v[96:111]
	global_load_lds_dwordx4 v253, s[22:23]
	ds_read_b64_tr_b16 v[140:141], v183 offset:4096
	ds_read_b64_tr_b16 v[142:143], v184 offset:6144
	v_mfma_f32_32x32x16_bf16 v[80:95], v[128:131], v[112:115], v[64:79]
	ds_read_b64_tr_b16 v[128:129], v174 offset:4096
	ds_read_b64_tr_b16 v[130:131], v175 offset:6144
	v_mfma_f32_32x32x16_bf16 v[80:95], v[136:139], v[116:119], v[80:95]
	s_nop 3
	v_mfma_f32_32x32x16_bf16 v[80:95], v[144:147], v[120:123], v[80:95]
	v_exp_f32_e32 v96, v96
	v_exp_f32_e32 v97, v97
	v_exp_f32_e32 v98, v98
	v_mfma_f32_32x32x16_bf16 v[80:95], v[152:155], v[124:127], v[80:95]
	v_exp_f32_e32 v99, v99
	v_exp_f32_e32 v100, v100
	v_exp_f32_e32 v101, v101
	v_exp_f32_e32 v102, v102
	v_exp_f32_e32 v103, v103
	v_cvt_pk_bf16_f32 v208, v96, v97
	v_cvt_pk_bf16_f32 v209, v98, v99
	v_cvt_pk_bf16_f32 v210, v100, v101
	v_cvt_pk_bf16_f32 v211, v102, v103
	v_exp_f32_e32 v104, v104
	v_exp_f32_e32 v105, v105
	s_waitcnt lgkmcnt(6)
	v_mfma_f32_32x32x16_bf16 v[48:63], v[224:227], v[208:211], v[48:63]
	v_exp_f32_e32 v106, v106
	v_exp_f32_e32 v107, v107
	v_exp_f32_e32 v108, v108
	ds_read_b64_tr_b16 v[136:137], v178 offset:4096
	ds_read_b64_tr_b16 v[138:139], v179 offset:6144
	v_mfma_f32_32x32x16_bf16 v[32:47], v[228:231], v[208:211], v[32:47]
	v_exp_f32_e32 v109, v109
	v_exp_f32_e32 v110, v110
	v_exp_f32_e32 v111, v111
	ds_read_b64_tr_b16 v[144:145], v174 offset:8192
	ds_read_b64_tr_b16 v[146:147], v175 offset:10240
	v_mfma_f32_32x32x16_bf16 v[16:31], v[232:235], v[208:211], v[16:31]
	v_cvt_pk_bf16_f32 v212, v104, v105
	v_cvt_pk_bf16_f32 v213, v106, v107
	v_cvt_pk_bf16_f32 v214, v108, v109
	v_cvt_pk_bf16_f32 v215, v110, v111
	v_add_f32_e32 v187, v96, v187
	v_add_f32_e32 v192, v97, v192
	ds_read_b64_tr_b16 v[148:149], v176 offset:8192
	ds_read_b64_tr_b16 v[150:151], v177 offset:10240
	v_mfma_f32_32x32x16_bf16 v[0:15], v[236:239], v[208:211], v[0:15]
	v_add_f32_e32 v193, v98, v193
	v_add_f32_e32 v194, v99, v194
	v_add_f32_e32 v187, v100, v187
	v_add_f32_e32 v192, v101, v192
	v_add_f32_e32 v193, v102, v193
	v_add_f32_e32 v194, v103, v194
	ds_read_b64_tr_b16 v[152:153], v178 offset:8192
	ds_read_b64_tr_b16 v[154:155], v179 offset:10240
	s_waitcnt lgkmcnt(6)
	v_mfma_f32_32x32x16_bf16 v[48:63], v[128:131], v[212:215], v[48:63]
	v_exp_f32_e32 v80, v80
	v_exp_f32_e32 v81, v81
	v_exp_f32_e32 v82, v82
	ds_read_b64_tr_b16 v[240:241], v183 offset:8192
	ds_read_b64_tr_b16 v[242:243], v184 offset:10240
	ds_read_b128 v[128:131], v188 offset:24576
	v_mfma_f32_32x32x16_bf16 v[32:47], v[132:135], v[212:215], v[32:47]
	v_exp_f32_e32 v83, v83
	v_exp_f32_e32 v84, v84
	v_exp_f32_e32 v85, v85
	ds_read_b64_tr_b16 v[196:197], v174 offset:12288
	ds_read_b64_tr_b16 v[198:199], v175 offset:14336
	ds_read_b128 v[132:135], v189 offset:16384
	v_mfma_f32_32x32x16_bf16 v[16:31], v[136:139], v[212:215], v[16:31]
	v_exp_f32_e32 v86, v86
	v_exp_f32_e32 v87, v87
	v_cvt_pk_bf16_f32 v216, v80, v81
	v_cvt_pk_bf16_f32 v217, v82, v83
	ds_read_b64_tr_b16 v[200:201], v176 offset:12288
	ds_read_b64_tr_b16 v[202:203], v177 offset:14336
	ds_read_b128 v[136:139], v189 offset:24576
	v_mfma_f32_32x32x16_bf16 v[0:15], v[140:143], v[212:215], v[0:15]
	v_cvt_pk_bf16_f32 v218, v84, v85
	v_cvt_pk_bf16_f32 v219, v86, v87
	v_add_f32_e32 v187, v104, v187
	v_add_f32_e32 v192, v105, v192
	v_add_f32_e32 v193, v106, v193
	v_add_f32_e32 v194, v107, v194
	s_waitcnt lgkmcnt(10)
	ds_read_b64_tr_b16 v[204:205], v178 offset:12288
	ds_read_b64_tr_b16 v[206:207], v179 offset:14336
	ds_read_b128 v[140:143], v190 offset:16384
	s_waitcnt lgkmcnt(10)
	v_mfma_f32_32x32x16_bf16 v[48:63], v[144:147], v[216:219], v[48:63]
	v_exp_f32_e32 v88, v88
	v_exp_f32_e32 v89, v89
	v_exp_f32_e32 v90, v90
	ds_read_b64_tr_b16 v[246:247], v183 offset:12288
	ds_read_b64_tr_b16 v[248:249], v184 offset:14336
	ds_read_b128 v[144:147], v190 offset:24576
	v_mfma_f32_32x32x16_bf16 v[32:47], v[148:151], v[216:219], v[32:47]
	v_exp_f32_e32 v91, v91
	v_exp_f32_e32 v92, v92
	v_exp_f32_e32 v93, v93
	ds_read_b128 v[148:151], v191 offset:16384
	v_mfma_f32_32x32x16_bf16 v[16:31], v[152:155], v[216:219], v[16:31]
	v_exp_f32_e32 v94, v94
	v_exp_f32_e32 v95, v95
	v_cvt_pk_bf16_f32 v220, v88, v89
	v_cvt_pk_bf16_f32 v221, v90, v91
	ds_read_b128 v[152:155], v191 offset:24576
	v_mfma_f32_32x32x16_bf16 v[0:15], v[240:243], v[216:219], v[0:15]
	v_cvt_pk_bf16_f32 v222, v92, v93
	v_cvt_pk_bf16_f32 v223, v94, v95
	v_add_f32_e32 v187, v80, v187
	v_add_f32_e32 v192, v81, v192
	v_add_f32_e32 v193, v82, v193
	v_add_f32_e32 v194, v83, v194
	s_waitcnt lgkmcnt(3)
	v_mfma_f32_32x32x16_bf16 v[48:63], v[196:199], v[220:223], v[48:63]
	v_add_f32_e32 v187, v108, v187
	v_add_f32_e32 v192, v109, v192
	v_add_f32_e32 v193, v110, v193
	v_add_f32_e32 v194, v111, v194
	v_add_f32_e32 v187, v84, v187
	v_add_f32_e32 v192, v85, v192
	ds_read_b128 v[80:83], v188 offset:16384
	v_mfma_f32_32x32x16_bf16 v[32:47], v[200:203], v[220:223], v[32:47]
	v_add_f32_e32 v193, v86, v193
	v_add_f32_e32 v194, v87, v194
	v_add_f32_e32 v187, v88, v187
	v_add_f32_e32 v192, v89, v192
	v_add_f32_e32 v193, v90, v193
	v_add_f32_e32 v194, v91, v194
	v_mfma_f32_32x32x16_bf16 v[16:31], v[204:207], v[220:223], v[16:31]
	v_add_f32_e32 v187, v92, v187
	v_add_f32_e32 v192, v93, v192
	v_add_f32_e32 v193, v94, v193
	v_add_f32_e32 v194, v95, v194
	v_mfma_f32_32x32x16_bf16 v[0:15], v[246:249], v[220:223], v[0:15]
	s_waitcnt vmcnt(4)
	s_waitcnt lgkmcnt(0)
	s_barrier
	s_add_i32 s10, s68, -3
	s_min_u32 s10, s10, s24
	s_lshl_b32 s10, s10, 15
	s_add_u32 s22, s20, s10
	s_addc_u32 s23, s21, 0
	ds_read_b64_tr_b16 v[224:225], v174 offset:16384
	ds_read_b64_tr_b16 v[226:227], v175 offset:18432
	ds_read_b64_tr_b16 v[228:229], v176 offset:16384
	ds_read_b64_tr_b16 v[230:231], v177 offset:18432
	ds_read_b64_tr_b16 v[232:233], v178 offset:16384
	ds_read_b64_tr_b16 v[234:235], v179 offset:18432
	ds_read_b64_tr_b16 v[236:237], v183 offset:16384
	ds_read_b64_tr_b16 v[238:239], v184 offset:18432
	s_mov_b32 m0, s43
	v_mfma_f32_32x32x16_bf16 v[96:111], v[132:135], v[116:119], v[64:79]
	global_load_lds_dwordx4 v163, s[22:23]
	s_mov_b32 m0, s45
	v_mfma_f32_32x32x16_bf16 v[96:111], v[140:143], v[120:123], v[96:111]
	global_load_lds_dwordx4 v254, s[22:23]
	s_mov_b32 m0, s25
	v_mfma_f32_32x32x16_bf16 v[96:111], v[148:151], v[124:127], v[96:111]
	global_load_lds_dwordx4 v255, s[4:5]
	ds_read_b64_tr_b16 v[132:133], v176 offset:20480
	ds_read_b64_tr_b16 v[134:135], v177 offset:22528
	s_mov_b32 m0, s63
	v_mfma_f32_32x32x16_bf16 v[96:111], v[80:83], v[112:115], v[96:111]
	global_load_lds_dwordx4 v253, s[4:5]
	ds_read_b64_tr_b16 v[140:141], v183 offset:20480
	ds_read_b64_tr_b16 v[142:143], v184 offset:22528
	v_mfma_f32_32x32x16_bf16 v[80:95], v[128:131], v[112:115], v[64:79]
	ds_read_b64_tr_b16 v[128:129], v174 offset:20480
	ds_read_b64_tr_b16 v[130:131], v175 offset:22528
	v_mfma_f32_32x32x16_bf16 v[80:95], v[136:139], v[116:119], v[80:95]
	s_nop 3
	v_mfma_f32_32x32x16_bf16 v[80:95], v[144:147], v[120:123], v[80:95]
	v_exp_f32_e32 v96, v96
	v_exp_f32_e32 v97, v97
	v_exp_f32_e32 v98, v98
	v_mfma_f32_32x32x16_bf16 v[80:95], v[152:155], v[124:127], v[80:95]
	v_exp_f32_e32 v99, v99
	v_exp_f32_e32 v100, v100
	v_exp_f32_e32 v101, v101
	v_exp_f32_e32 v102, v102
	v_exp_f32_e32 v103, v103
	v_cvt_pk_bf16_f32 v208, v96, v97
	v_cvt_pk_bf16_f32 v209, v98, v99
	v_cvt_pk_bf16_f32 v210, v100, v101
	v_cvt_pk_bf16_f32 v211, v102, v103
	v_exp_f32_e32 v104, v104
	v_exp_f32_e32 v105, v105
	s_waitcnt lgkmcnt(6)
	v_mfma_f32_32x32x16_bf16 v[48:63], v[224:227], v[208:211], v[48:63]
	v_exp_f32_e32 v106, v106
	v_exp_f32_e32 v107, v107
	v_exp_f32_e32 v108, v108
	ds_read_b64_tr_b16 v[136:137], v178 offset:20480
	ds_read_b64_tr_b16 v[138:139], v179 offset:22528
	v_mfma_f32_32x32x16_bf16 v[32:47], v[228:231], v[208:211], v[32:47]
	v_exp_f32_e32 v109, v109
	v_exp_f32_e32 v110, v110
	v_exp_f32_e32 v111, v111
	ds_read_b64_tr_b16 v[144:145], v174 offset:24576
	ds_read_b64_tr_b16 v[146:147], v175 offset:26624
	v_mfma_f32_32x32x16_bf16 v[16:31], v[232:235], v[208:211], v[16:31]
	v_cvt_pk_bf16_f32 v212, v104, v105
	v_cvt_pk_bf16_f32 v213, v106, v107
	v_cvt_pk_bf16_f32 v214, v108, v109
	v_cvt_pk_bf16_f32 v215, v110, v111
	v_add_f32_e32 v187, v96, v187
	v_add_f32_e32 v192, v97, v192
	ds_read_b64_tr_b16 v[148:149], v176 offset:24576
	ds_read_b64_tr_b16 v[150:151], v177 offset:26624
	v_mfma_f32_32x32x16_bf16 v[0:15], v[236:239], v[208:211], v[0:15]
	v_add_f32_e32 v193, v98, v193
	v_add_f32_e32 v194, v99, v194
	v_add_f32_e32 v187, v100, v187
	v_add_f32_e32 v192, v101, v192
	v_add_f32_e32 v193, v102, v193
	v_add_f32_e32 v194, v103, v194
	ds_read_b64_tr_b16 v[152:153], v178 offset:24576
	ds_read_b64_tr_b16 v[154:155], v179 offset:26624
	s_waitcnt lgkmcnt(6)
	v_mfma_f32_32x32x16_bf16 v[48:63], v[128:131], v[212:215], v[48:63]
	v_exp_f32_e32 v80, v80
	v_exp_f32_e32 v81, v81
	v_exp_f32_e32 v82, v82
	ds_read_b64_tr_b16 v[240:241], v183 offset:24576
	ds_read_b64_tr_b16 v[242:243], v184 offset:26624
	ds_read_b128 v[128:131], v188 offset:40960
	v_mfma_f32_32x32x16_bf16 v[32:47], v[132:135], v[212:215], v[32:47]
	v_exp_f32_e32 v83, v83
	v_exp_f32_e32 v84, v84
	v_exp_f32_e32 v85, v85
	ds_read_b64_tr_b16 v[196:197], v174 offset:28672
	ds_read_b64_tr_b16 v[198:199], v175 offset:30720
	ds_read_b128 v[132:135], v189 offset:32768
	v_mfma_f32_32x32x16_bf16 v[16:31], v[136:139], v[212:215], v[16:31]
	v_exp_f32_e32 v86, v86
	v_exp_f32_e32 v87, v87
	v_cvt_pk_bf16_f32 v216, v80, v81
	v_cvt_pk_bf16_f32 v217, v82, v83
	ds_read_b64_tr_b16 v[200:201], v176 offset:28672
	ds_read_b64_tr_b16 v[202:203], v177 offset:30720
	ds_read_b128 v[136:139], v189 offset:40960
	v_mfma_f32_32x32x16_bf16 v[0:15], v[140:143], v[212:215], v[0:15]
	v_cvt_pk_bf16_f32 v218, v84, v85
	v_cvt_pk_bf16_f32 v219, v86, v87
	v_add_f32_e32 v187, v104, v187
	v_add_f32_e32 v192, v105, v192
	v_add_f32_e32 v193, v106, v193
	v_add_f32_e32 v194, v107, v194
	s_waitcnt lgkmcnt(10)
	ds_read_b64_tr_b16 v[204:205], v178 offset:28672
	ds_read_b64_tr_b16 v[206:207], v179 offset:30720
	ds_read_b128 v[140:143], v190 offset:32768
	s_waitcnt lgkmcnt(10)
	v_mfma_f32_32x32x16_bf16 v[48:63], v[144:147], v[216:219], v[48:63]
	v_exp_f32_e32 v88, v88
	v_exp_f32_e32 v89, v89
	v_exp_f32_e32 v90, v90
	ds_read_b64_tr_b16 v[246:247], v183 offset:28672
	ds_read_b64_tr_b16 v[248:249], v184 offset:30720
	ds_read_b128 v[144:147], v190 offset:40960
	v_mfma_f32_32x32x16_bf16 v[32:47], v[148:151], v[216:219], v[32:47]
	v_exp_f32_e32 v91, v91
	v_exp_f32_e32 v92, v92
	v_exp_f32_e32 v93, v93
	ds_read_b128 v[148:151], v191 offset:32768
	v_mfma_f32_32x32x16_bf16 v[16:31], v[152:155], v[216:219], v[16:31]
	v_exp_f32_e32 v94, v94
	v_exp_f32_e32 v95, v95
	v_cvt_pk_bf16_f32 v220, v88, v89
	v_cvt_pk_bf16_f32 v221, v90, v91
	ds_read_b128 v[152:155], v191 offset:40960
	v_mfma_f32_32x32x16_bf16 v[0:15], v[240:243], v[216:219], v[0:15]
	v_cvt_pk_bf16_f32 v222, v92, v93
	v_cvt_pk_bf16_f32 v223, v94, v95
	v_add_f32_e32 v187, v80, v187
	v_add_f32_e32 v192, v81, v192
	v_add_f32_e32 v193, v82, v193
	v_add_f32_e32 v194, v83, v194
	s_waitcnt lgkmcnt(3)
	v_mfma_f32_32x32x16_bf16 v[48:63], v[196:199], v[220:223], v[48:63]
	v_add_f32_e32 v187, v108, v187
	v_add_f32_e32 v192, v109, v192
	v_add_f32_e32 v193, v110, v193
	v_add_f32_e32 v194, v111, v194
	v_add_f32_e32 v187, v84, v187
	v_add_f32_e32 v192, v85, v192
	ds_read_b128 v[80:83], v188 offset:32768
	v_mfma_f32_32x32x16_bf16 v[32:47], v[200:203], v[220:223], v[32:47]
	v_add_f32_e32 v193, v86, v193
	v_add_f32_e32 v194, v87, v194
	v_add_f32_e32 v187, v88, v187
	v_add_f32_e32 v192, v89, v192
	v_add_f32_e32 v193, v90, v193
	v_add_f32_e32 v194, v91, v194
	v_mfma_f32_32x32x16_bf16 v[16:31], v[204:207], v[220:223], v[16:31]
	v_add_f32_e32 v187, v92, v187
	v_add_f32_e32 v192, v93, v192
	v_add_f32_e32 v193, v94, v193
	v_add_f32_e32 v194, v95, v194
	v_mfma_f32_32x32x16_bf16 v[0:15], v[246:249], v[220:223], v[0:15]
	s_waitcnt vmcnt(4)
	s_waitcnt lgkmcnt(0)
	s_barrier
	s_add_i32 s10, s68, -2
	s_min_u32 s10, s10, s24
	s_lshl_b32 s10, s10, 15
	s_add_u32 s4, s20, s10
	s_addc_u32 s5, s21, 0
	ds_read_b64_tr_b16 v[224:225], v174 offset:32768
	ds_read_b64_tr_b16 v[226:227], v175 offset:34816
	ds_read_b64_tr_b16 v[228:229], v176 offset:32768
	ds_read_b64_tr_b16 v[230:231], v177 offset:34816
	ds_read_b64_tr_b16 v[232:233], v178 offset:32768
	ds_read_b64_tr_b16 v[234:235], v179 offset:34816
	ds_read_b64_tr_b16 v[236:237], v183 offset:32768
	ds_read_b64_tr_b16 v[238:239], v184 offset:34816
	s_mov_b32 m0, s46
	v_mfma_f32_32x32x16_bf16 v[96:111], v[132:135], v[116:119], v[64:79]
	global_load_lds_dwordx4 v163, s[4:5]
	s_mov_b32 m0, s47
	v_mfma_f32_32x32x16_bf16 v[96:111], v[140:143], v[120:123], v[96:111]
	global_load_lds_dwordx4 v254, s[4:5]
	s_mov_b32 m0, s44
	v_mfma_f32_32x32x16_bf16 v[96:111], v[148:151], v[124:127], v[96:111]
	global_load_lds_dwordx4 v255, s[22:23]
	ds_read_b64_tr_b16 v[132:133], v176 offset:36864
	ds_read_b64_tr_b16 v[134:135], v177 offset:38912
	s_mov_b32 m0, s48
	v_mfma_f32_32x32x16_bf16 v[96:111], v[80:83], v[112:115], v[96:111]
	global_load_lds_dwordx4 v253, s[22:23]
	ds_read_b64_tr_b16 v[140:141], v183 offset:36864
	ds_read_b64_tr_b16 v[142:143], v184 offset:38912
	v_mfma_f32_32x32x16_bf16 v[80:95], v[128:131], v[112:115], v[64:79]
	ds_read_b64_tr_b16 v[128:129], v174 offset:36864
	ds_read_b64_tr_b16 v[130:131], v175 offset:38912
	v_mfma_f32_32x32x16_bf16 v[80:95], v[136:139], v[116:119], v[80:95]
	s_nop 3
	v_mfma_f32_32x32x16_bf16 v[80:95], v[144:147], v[120:123], v[80:95]
	v_exp_f32_e32 v96, v96
	v_exp_f32_e32 v97, v97
	v_exp_f32_e32 v98, v98
	v_mfma_f32_32x32x16_bf16 v[80:95], v[152:155], v[124:127], v[80:95]
	v_exp_f32_e32 v99, v99
	v_exp_f32_e32 v100, v100
	v_exp_f32_e32 v101, v101
	v_exp_f32_e32 v102, v102
	v_exp_f32_e32 v103, v103
	v_cvt_pk_bf16_f32 v208, v96, v97
	v_cvt_pk_bf16_f32 v209, v98, v99
	v_cvt_pk_bf16_f32 v210, v100, v101
	v_cvt_pk_bf16_f32 v211, v102, v103
	v_exp_f32_e32 v104, v104
	v_exp_f32_e32 v105, v105
	s_waitcnt lgkmcnt(6)
	v_mfma_f32_32x32x16_bf16 v[48:63], v[224:227], v[208:211], v[48:63]
	v_exp_f32_e32 v106, v106
	v_exp_f32_e32 v107, v107
	v_exp_f32_e32 v108, v108
	ds_read_b64_tr_b16 v[136:137], v178 offset:36864
	ds_read_b64_tr_b16 v[138:139], v179 offset:38912
	v_mfma_f32_32x32x16_bf16 v[32:47], v[228:231], v[208:211], v[32:47]
	v_exp_f32_e32 v109, v109
	v_exp_f32_e32 v110, v110
	v_exp_f32_e32 v111, v111
	ds_read_b64_tr_b16 v[144:145], v174 offset:40960
	ds_read_b64_tr_b16 v[146:147], v175 offset:43008
	v_mfma_f32_32x32x16_bf16 v[16:31], v[232:235], v[208:211], v[16:31]
	v_cvt_pk_bf16_f32 v212, v104, v105
	v_cvt_pk_bf16_f32 v213, v106, v107
	v_cvt_pk_bf16_f32 v214, v108, v109
	v_cvt_pk_bf16_f32 v215, v110, v111
	v_add_f32_e32 v187, v96, v187
	v_add_f32_e32 v192, v97, v192
	ds_read_b64_tr_b16 v[148:149], v176 offset:40960
	ds_read_b64_tr_b16 v[150:151], v177 offset:43008
	v_mfma_f32_32x32x16_bf16 v[0:15], v[236:239], v[208:211], v[0:15]
	v_add_f32_e32 v193, v98, v193
	v_add_f32_e32 v194, v99, v194
	v_add_f32_e32 v187, v100, v187
	v_add_f32_e32 v192, v101, v192
	v_add_f32_e32 v193, v102, v193
	v_add_f32_e32 v194, v103, v194
	ds_read_b64_tr_b16 v[152:153], v178 offset:40960
	ds_read_b64_tr_b16 v[154:155], v179 offset:43008
	s_waitcnt lgkmcnt(6)
	v_mfma_f32_32x32x16_bf16 v[48:63], v[128:131], v[212:215], v[48:63]
	v_exp_f32_e32 v80, v80
	v_exp_f32_e32 v81, v81
	v_exp_f32_e32 v82, v82
	ds_read_b64_tr_b16 v[240:241], v183 offset:40960
	ds_read_b64_tr_b16 v[242:243], v184 offset:43008
	ds_read_b128 v[128:131], v188 offset:57344
	v_mfma_f32_32x32x16_bf16 v[32:47], v[132:135], v[212:215], v[32:47]
	v_exp_f32_e32 v83, v83
	v_exp_f32_e32 v84, v84
	v_exp_f32_e32 v85, v85
	ds_read_b64_tr_b16 v[196:197], v174 offset:45056
	ds_read_b64_tr_b16 v[198:199], v175 offset:47104
	ds_read_b128 v[132:135], v189 offset:49152
	v_mfma_f32_32x32x16_bf16 v[16:31], v[136:139], v[212:215], v[16:31]
	v_exp_f32_e32 v86, v86
	v_exp_f32_e32 v87, v87
	v_cvt_pk_bf16_f32 v216, v80, v81
	v_cvt_pk_bf16_f32 v217, v82, v83
	ds_read_b64_tr_b16 v[200:201], v176 offset:45056
	ds_read_b64_tr_b16 v[202:203], v177 offset:47104
	ds_read_b128 v[136:139], v189 offset:57344
	v_mfma_f32_32x32x16_bf16 v[0:15], v[140:143], v[212:215], v[0:15]
	v_cvt_pk_bf16_f32 v218, v84, v85
	v_cvt_pk_bf16_f32 v219, v86, v87
	v_add_f32_e32 v187, v104, v187
	v_add_f32_e32 v192, v105, v192
	v_add_f32_e32 v193, v106, v193
	v_add_f32_e32 v194, v107, v194
	s_waitcnt lgkmcnt(10)
	ds_read_b64_tr_b16 v[204:205], v178 offset:45056
	ds_read_b64_tr_b16 v[206:207], v179 offset:47104
	ds_read_b128 v[140:143], v190 offset:49152
	s_waitcnt lgkmcnt(10)
	v_mfma_f32_32x32x16_bf16 v[48:63], v[144:147], v[216:219], v[48:63]
	v_exp_f32_e32 v88, v88
	v_exp_f32_e32 v89, v89
	v_exp_f32_e32 v90, v90
	ds_read_b64_tr_b16 v[246:247], v183 offset:45056
	ds_read_b64_tr_b16 v[248:249], v184 offset:47104
	ds_read_b128 v[144:147], v190 offset:57344
	v_mfma_f32_32x32x16_bf16 v[32:47], v[148:151], v[216:219], v[32:47]
	v_exp_f32_e32 v91, v91
	v_exp_f32_e32 v92, v92
	v_exp_f32_e32 v93, v93
	ds_read_b128 v[148:151], v191 offset:49152
	v_mfma_f32_32x32x16_bf16 v[16:31], v[152:155], v[216:219], v[16:31]
	v_exp_f32_e32 v94, v94
	v_exp_f32_e32 v95, v95
	v_cvt_pk_bf16_f32 v220, v88, v89
	v_cvt_pk_bf16_f32 v221, v90, v91
	ds_read_b128 v[152:155], v191 offset:57344
	v_mfma_f32_32x32x16_bf16 v[0:15], v[240:243], v[216:219], v[0:15]
	v_cvt_pk_bf16_f32 v222, v92, v93
	v_cvt_pk_bf16_f32 v223, v94, v95
	v_add_f32_e32 v187, v80, v187
	v_add_f32_e32 v192, v81, v192
	v_add_f32_e32 v193, v82, v193
	v_add_f32_e32 v194, v83, v194
	s_waitcnt lgkmcnt(3)
	v_mfma_f32_32x32x16_bf16 v[48:63], v[196:199], v[220:223], v[48:63]
	v_add_f32_e32 v187, v108, v187
	v_add_f32_e32 v192, v109, v192
	v_add_f32_e32 v193, v110, v193
	v_add_f32_e32 v194, v111, v194
	v_add_f32_e32 v187, v84, v187
	v_add_f32_e32 v192, v85, v192
	ds_read_b128 v[80:83], v188 offset:49152
	v_mfma_f32_32x32x16_bf16 v[32:47], v[200:203], v[220:223], v[32:47]
	v_add_f32_e32 v193, v86, v193
	v_add_f32_e32 v194, v87, v194
	v_add_f32_e32 v187, v88, v187
	v_add_f32_e32 v192, v89, v192
	v_add_f32_e32 v193, v90, v193
	v_add_f32_e32 v194, v91, v194
	v_mfma_f32_32x32x16_bf16 v[16:31], v[204:207], v[220:223], v[16:31]
	v_add_f32_e32 v187, v92, v187
	v_add_f32_e32 v192, v93, v192
	v_add_f32_e32 v193, v94, v193
	v_add_f32_e32 v194, v95, v194
	v_mfma_f32_32x32x16_bf16 v[0:15], v[246:249], v[220:223], v[0:15]
	s_waitcnt vmcnt(4)
	s_waitcnt lgkmcnt(0)
	s_barrier
	s_add_i32 s10, s68, -1
	s_min_u32 s10, s10, s24
	s_lshl_b32 s10, s10, 15
	s_add_u32 s22, s20, s10
	s_addc_u32 s23, s21, 0
	ds_read_b64_tr_b16 v[224:225], v174 offset:49152
	ds_read_b64_tr_b16 v[226:227], v175 offset:51200
	ds_read_b64_tr_b16 v[228:229], v176 offset:49152
	ds_read_b64_tr_b16 v[230:231], v177 offset:51200
	ds_read_b64_tr_b16 v[232:233], v178 offset:49152
	ds_read_b64_tr_b16 v[234:235], v179 offset:51200
	ds_read_b64_tr_b16 v[236:237], v183 offset:49152
	ds_read_b64_tr_b16 v[238:239], v184 offset:51200
	s_mov_b32 m0, s49
	v_mfma_f32_32x32x16_bf16 v[96:111], v[132:135], v[116:119], v[64:79]
	global_load_lds_dwordx4 v163, s[22:23]
	s_mov_b32 m0, s50
	v_mfma_f32_32x32x16_bf16 v[96:111], v[140:143], v[120:123], v[96:111]
	global_load_lds_dwordx4 v254, s[22:23]
	s_mov_b32 m0, s51
	v_mfma_f32_32x32x16_bf16 v[96:111], v[148:151], v[124:127], v[96:111]
	global_load_lds_dwordx4 v255, s[4:5]
	ds_read_b64_tr_b16 v[132:133], v176 offset:53248
	ds_read_b64_tr_b16 v[134:135], v177 offset:55296
	s_mov_b32 m0, s52
	v_mfma_f32_32x32x16_bf16 v[96:111], v[80:83], v[112:115], v[96:111]
	global_load_lds_dwordx4 v253, s[4:5]
	ds_read_b64_tr_b16 v[140:141], v183 offset:53248
	ds_read_b64_tr_b16 v[142:143], v184 offset:55296
	v_mfma_f32_32x32x16_bf16 v[80:95], v[128:131], v[112:115], v[64:79]
	ds_read_b64_tr_b16 v[128:129], v174 offset:53248
	ds_read_b64_tr_b16 v[130:131], v175 offset:55296
	v_mfma_f32_32x32x16_bf16 v[80:95], v[136:139], v[116:119], v[80:95]
	s_nop 3
	v_mfma_f32_32x32x16_bf16 v[80:95], v[144:147], v[120:123], v[80:95]
	v_exp_f32_e32 v96, v96
	v_exp_f32_e32 v97, v97
	v_exp_f32_e32 v98, v98
	v_mfma_f32_32x32x16_bf16 v[80:95], v[152:155], v[124:127], v[80:95]
	v_exp_f32_e32 v99, v99
	v_exp_f32_e32 v100, v100
	v_exp_f32_e32 v101, v101
	v_exp_f32_e32 v102, v102
	v_exp_f32_e32 v103, v103
	v_cvt_pk_bf16_f32 v208, v96, v97
	v_cvt_pk_bf16_f32 v209, v98, v99
	v_cvt_pk_bf16_f32 v210, v100, v101
	v_cvt_pk_bf16_f32 v211, v102, v103
	v_exp_f32_e32 v104, v104
	v_exp_f32_e32 v105, v105
	s_waitcnt lgkmcnt(6)
	v_mfma_f32_32x32x16_bf16 v[48:63], v[224:227], v[208:211], v[48:63]
	v_exp_f32_e32 v106, v106
	v_exp_f32_e32 v107, v107
	v_exp_f32_e32 v108, v108
	ds_read_b64_tr_b16 v[136:137], v178 offset:53248
	ds_read_b64_tr_b16 v[138:139], v179 offset:55296
	v_mfma_f32_32x32x16_bf16 v[32:47], v[228:231], v[208:211], v[32:47]
	v_exp_f32_e32 v109, v109
	v_exp_f32_e32 v110, v110
	v_exp_f32_e32 v111, v111
	ds_read_b64_tr_b16 v[144:145], v174 offset:57344
	ds_read_b64_tr_b16 v[146:147], v175 offset:59392
	v_mfma_f32_32x32x16_bf16 v[16:31], v[232:235], v[208:211], v[16:31]
	v_cvt_pk_bf16_f32 v212, v104, v105
	v_cvt_pk_bf16_f32 v213, v106, v107
	v_cvt_pk_bf16_f32 v214, v108, v109
	v_cvt_pk_bf16_f32 v215, v110, v111
	v_add_f32_e32 v187, v96, v187
	v_add_f32_e32 v192, v97, v192
	ds_read_b64_tr_b16 v[148:149], v176 offset:57344
	ds_read_b64_tr_b16 v[150:151], v177 offset:59392
	v_mfma_f32_32x32x16_bf16 v[0:15], v[236:239], v[208:211], v[0:15]
	v_add_f32_e32 v193, v98, v193
	v_add_f32_e32 v194, v99, v194
	v_add_f32_e32 v187, v100, v187
	v_add_f32_e32 v192, v101, v192
	v_add_f32_e32 v193, v102, v193
	v_add_f32_e32 v194, v103, v194
	ds_read_b64_tr_b16 v[152:153], v178 offset:57344
	ds_read_b64_tr_b16 v[154:155], v179 offset:59392
	s_waitcnt lgkmcnt(6)
	v_mfma_f32_32x32x16_bf16 v[48:63], v[128:131], v[212:215], v[48:63]
	v_exp_f32_e32 v80, v80
	v_exp_f32_e32 v81, v81
	v_exp_f32_e32 v82, v82
	ds_read_b64_tr_b16 v[240:241], v183 offset:57344
	ds_read_b64_tr_b16 v[242:243], v184 offset:59392
	ds_read_b128 v[128:131], v188 offset:8192
	v_mfma_f32_32x32x16_bf16 v[32:47], v[132:135], v[212:215], v[32:47]
	v_exp_f32_e32 v83, v83
	v_exp_f32_e32 v84, v84
	v_exp_f32_e32 v85, v85
	ds_read_b64_tr_b16 v[196:197], v174 offset:61440
	ds_read_b64_tr_b16 v[198:199], v175 offset:63488
	ds_read_b128 v[132:135], v189
	v_mfma_f32_32x32x16_bf16 v[16:31], v[136:139], v[212:215], v[16:31]
	v_exp_f32_e32 v86, v86
	v_exp_f32_e32 v87, v87
	v_cvt_pk_bf16_f32 v216, v80, v81
	v_cvt_pk_bf16_f32 v217, v82, v83
	ds_read_b64_tr_b16 v[200:201], v176 offset:61440
	ds_read_b64_tr_b16 v[202:203], v177 offset:63488
	ds_read_b128 v[136:139], v189 offset:8192
	v_mfma_f32_32x32x16_bf16 v[0:15], v[140:143], v[212:215], v[0:15]
	v_cvt_pk_bf16_f32 v218, v84, v85
	v_cvt_pk_bf16_f32 v219, v86, v87
	v_add_f32_e32 v187, v104, v187
	v_add_f32_e32 v192, v105, v192
	v_add_f32_e32 v193, v106, v193
	v_add_f32_e32 v194, v107, v194
	s_waitcnt lgkmcnt(10)
	ds_read_b64_tr_b16 v[204:205], v178 offset:61440
	ds_read_b64_tr_b16 v[206:207], v179 offset:63488
	ds_read_b128 v[140:143], v190
	s_waitcnt lgkmcnt(10)
	v_mfma_f32_32x32x16_bf16 v[48:63], v[144:147], v[216:219], v[48:63]
	v_exp_f32_e32 v88, v88
	v_exp_f32_e32 v89, v89
	v_exp_f32_e32 v90, v90
	ds_read_b64_tr_b16 v[246:247], v183 offset:61440
	ds_read_b64_tr_b16 v[248:249], v184 offset:63488
	ds_read_b128 v[144:147], v190 offset:8192
	v_mfma_f32_32x32x16_bf16 v[32:47], v[148:151], v[216:219], v[32:47]
	v_exp_f32_e32 v91, v91
	v_exp_f32_e32 v92, v92
	v_exp_f32_e32 v93, v93
	ds_read_b128 v[148:151], v191
	v_mfma_f32_32x32x16_bf16 v[16:31], v[152:155], v[216:219], v[16:31]
	v_exp_f32_e32 v94, v94
	v_exp_f32_e32 v95, v95
	v_cvt_pk_bf16_f32 v220, v88, v89
	v_cvt_pk_bf16_f32 v221, v90, v91
	ds_read_b128 v[152:155], v191 offset:8192
	v_mfma_f32_32x32x16_bf16 v[0:15], v[240:243], v[216:219], v[0:15]
	v_cvt_pk_bf16_f32 v222, v92, v93
	v_cvt_pk_bf16_f32 v223, v94, v95
	v_add_f32_e32 v187, v80, v187
	v_add_f32_e32 v192, v81, v192
	v_add_f32_e32 v193, v82, v193
	v_add_f32_e32 v194, v83, v194
	s_waitcnt lgkmcnt(3)
	v_mfma_f32_32x32x16_bf16 v[48:63], v[196:199], v[220:223], v[48:63]
	v_add_f32_e32 v187, v108, v187
	v_add_f32_e32 v192, v109, v192
	v_add_f32_e32 v193, v110, v193
	v_add_f32_e32 v194, v111, v194
	v_add_f32_e32 v187, v84, v187
	v_add_f32_e32 v192, v85, v192
	ds_read_b128 v[80:83], v188
	v_mfma_f32_32x32x16_bf16 v[32:47], v[200:203], v[220:223], v[32:47]
	v_add_f32_e32 v193, v86, v193
	v_add_f32_e32 v194, v87, v194
	v_add_f32_e32 v187, v88, v187
	v_add_f32_e32 v192, v89, v192
	v_add_f32_e32 v193, v90, v193
	v_add_f32_e32 v194, v91, v194
	v_mfma_f32_32x32x16_bf16 v[16:31], v[204:207], v[220:223], v[16:31]
	v_add_f32_e32 v187, v92, v187
	v_add_f32_e32 v192, v93, v192
	v_add_f32_e32 v193, v94, v193
	v_add_f32_e32 v194, v95, v194
	v_mfma_f32_32x32x16_bf16 v[0:15], v[246:249], v[220:223], v[0:15]
	s_waitcnt vmcnt(4)
	s_add_i32 s68, s68, 4
	s_cmp_ge_u32 s69, s42
	s_waitcnt lgkmcnt(0)
	s_barrier
; #define LAS __attribute__((address_space(3)))
; __device__ __forceinline__ void attn_unit(LAS unsigned char* L, bf16_t* QKV, size_t rowbase, int S, int h, int qb, float lam, const float* subln, unsigned* kmax) {
;     ...
;     lsum = (lsum + lsb) + (lsc + lsd);
;     const float inv = 1.f / (lsum + __shfl_xor(lsum, 32));
;     LAS float* X = (LAS float*)L;
;     const int xo = (32 * qblk + r32) * AXP + 4 * hi;
;     if (hd == 1) { const float sc = inv * lam;
; #pragma unroll
;         for (int d = 0; d < 4; ++d)
; #pragma unroll
;             for (int rg = 0; rg < 4; ++rg) *(LAS f32x4*)(X + xo + 32 * d + 8 * rg) = (f32x4){o[d][4 * rg] * sc, o[d][4 * rg + 1] * sc, o[d][4 * rg + 2] * sc, o[d][4 * rg + 3] * sc}; }
	s_cbranch_scc0 .LBB0_927
	s_setprio 0
	v_add_f32_e32 v64, v187, v192
	v_add_f32_e32 v65, v193, v194
	v_add_f32_e32 v64, v64, v65
	ds_bpermute_b32 v65, v156, v64
	s_waitcnt vmcnt(0)
	s_cmp_eq_u32 s40, 1
	s_waitcnt lgkmcnt(0)
	s_barrier
	v_add_f32_e32 v64, v64, v65
	v_div_scale_f32 v65, s[4:5], v64, v64, 1.0
	v_rcp_f32_e32 v66, v65
	s_nop 0
	v_fma_f32 v67, -v65, v66, 1.0
	v_fmac_f32_e32 v66, v67, v66
	v_div_scale_f32 v67, vcc, 1.0, v64, 1.0
	v_mul_f32_e32 v68, v67, v66
	v_fma_f32 v69, -v65, v68, v67
	v_fmac_f32_e32 v68, v69, v66
	v_fma_f32 v65, -v65, v68, v67
	v_div_fmas_f32 v65, v65, v66, v68
	v_div_fixup_f32 v66, v65, v64, 1.0
	v_or_b32_e32 v64, s41, v182
	v_mad_u32_u24 v64, v64, s38, v158
	v_lshl_add_u32 v64, v64, 2, 0
	s_cbranch_scc0 .LBB0_930
	v_mul_f32_e32 v72, v159, v66
	v_pk_mul_f32 v[68:69], v[48:49], v[72:73] op_sel_hi:[1,0]
	v_pk_mul_f32 v[70:71], v[50:51], v[72:73] op_sel_hi:[1,0]
	ds_write_b128 v64, v[68:71]
	v_pk_mul_f32 v[68:69], v[52:53], v[72:73] op_sel_hi:[1,0]
	v_pk_mul_f32 v[70:71], v[54:55], v[72:73] op_sel_hi:[1,0]
	ds_write_b128 v64, v[68:71] offset:32
	v_pk_mul_f32 v[68:69], v[56:57], v[72:73] op_sel_hi:[1,0]
	v_pk_mul_f32 v[70:71], v[58:59], v[72:73] op_sel_hi:[1,0]
	ds_write_b128 v64, v[68:71] offset:64
	v_pk_mul_f32 v[68:69], v[60:61], v[72:73] op_sel_hi:[1,0]
	v_pk_mul_f32 v[70:71], v[62:63], v[72:73] op_sel_hi:[1,0]
	ds_write_b128 v64, v[68:71] offset:96
	v_pk_mul_f32 v[68:69], v[32:33], v[72:73] op_sel_hi:[1,0]
	v_pk_mul_f32 v[70:71], v[34:35], v[72:73] op_sel_hi:[1,0]
	ds_write_b128 v64, v[68:71] offset:128
	v_pk_mul_f32 v[68:69], v[36:37], v[72:73] op_sel_hi:[1,0]
	v_pk_mul_f32 v[70:71], v[38:39], v[72:73] op_sel_hi:[1,0]
	ds_write_b128 v64, v[68:71] offset:160
	v_pk_mul_f32 v[68:69], v[40:41], v[72:73] op_sel_hi:[1,0]
	v_pk_mul_f32 v[70:71], v[42:43], v[72:73] op_sel_hi:[1,0]
	ds_write_b128 v64, v[68:71] offset:192
	v_pk_mul_f32 v[68:69], v[44:45], v[72:73] op_sel_hi:[1,0]
	v_pk_mul_f32 v[70:71], v[46:47], v[72:73] op_sel_hi:[1,0]
	ds_write_b128 v64, v[68:71] offset:224
	v_pk_mul_f32 v[68:69], v[16:17], v[72:73] op_sel_hi:[1,0]
	v_pk_mul_f32 v[70:71], v[18:19], v[72:73] op_sel_hi:[1,0]
	ds_write_b128 v64, v[68:71] offset:256
	v_pk_mul_f32 v[68:69], v[20:21], v[72:73] op_sel_hi:[1,0]
	v_pk_mul_f32 v[70:71], v[22:23], v[72:73] op_sel_hi:[1,0]
	ds_write_b128 v64, v[68:71] offset:288
	v_pk_mul_f32 v[68:69], v[24:25], v[72:73] op_sel_hi:[1,0]
	v_pk_mul_f32 v[70:71], v[26:27], v[72:73] op_sel_hi:[1,0]
	ds_write_b128 v64, v[68:71] offset:320
	v_pk_mul_f32 v[68:69], v[28:29], v[72:73] op_sel_hi:[1,0]
	v_pk_mul_f32 v[70:71], v[30:31], v[72:73] op_sel_hi:[1,0]
	ds_write_b128 v64, v[68:71] offset:352
	v_pk_mul_f32 v[68:69], v[0:1], v[72:73] op_sel_hi:[1,0]
	v_pk_mul_f32 v[70:71], v[2:3], v[72:73] op_sel_hi:[1,0]
	ds_write_b128 v64, v[68:71] offset:384
	v_pk_mul_f32 v[68:69], v[4:5], v[72:73] op_sel_hi:[1,0]
	v_pk_mul_f32 v[70:71], v[6:7], v[72:73] op_sel_hi:[1,0]
	ds_write_b128 v64, v[68:71] offset:416
	v_pk_mul_f32 v[68:69], v[8:9], v[72:73] op_sel_hi:[1,0]
	v_pk_mul_f32 v[70:71], v[10:11], v[72:73] op_sel_hi:[1,0]
	ds_write_b128 v64, v[68:71] offset:448
	v_pk_mul_f32 v[68:69], v[12:13], v[72:73] op_sel_hi:[1,0]
	v_pk_mul_f32 v[70:71], v[14:15], v[72:73] op_sel_hi:[1,0]
	ds_write_b128 v64, v[68:71] offset:480
